# attention pass 1: previous-accumulator loads widened to dwordx4 + permlane16_swap
# speedup vs baseline: 1.0280x; 1.0004x over previous
; __device__ __forceinline__ unsigned cvt_pk_bf16(float lo, float hi) { unsigned r; asm volatile("v_cvt_pk_bf16_f32 %0, %1, %2" : "=v"(r) : "v"(lo), "v"(hi)); return r; }
;     ...
;         const float rl = 1.0f / l;
;         float Lc = mx + __builtin_amdgcn_logf(l);
;         float wb = rl, wa = 0.f;
;         if (PASS > 0) { const float Lm = fmaxf(Lp, Lc);
;             const float ea = __builtin_amdgcn_exp2f(Lp - Lm), eb = __builtin_amdgcn_exp2f(Lc - Lm), den = ea + eb, rd = 1.0f / den;
;             wa = ea * rd; wb = eb * rd * rl; Lc = Lm + __builtin_amdgcn_logf(den); }
;         if (PASS < 2) { if (fq == 0) LACC[(size_t)qrow * 16 + h] = Lc; }
; #pragma unroll
;         for (int db = 0; db < 8; ++db) { f32x4 v = o[db] * wb;
;             const size_t ocol = (size_t)h * 128 + 16 * db + 4 * fq;
;             if (PASS > 0) { v[0] += wa * bf_lo(pv[db].x); v[1] += wa * bf_hi(pv[db].x); v[2] += wa * bf_lo(pv[db].y); v[3] += wa * bf_hi(pv[db].y); }
;             if (PASS < 2) { u32x2 ov; ov.x = pg8::cvt_pk_bf16(v[0], v[1]); ov.y = pg8::cvt_pk_bf16(v[2], v[3]); *(u32x2*)((char*)OACC + ((unsigned)(h * MT + qrow) * 256u + (unsigned)(32 * db + 8 * fq))) = ov; }
.LBB0_364:
	s_or_b64 exec, exec, s[0:1]
	v_div_scale_f32 v90, s[0:1], v87, v87, 1.0
	v_rcp_f32_e32 v91, v90
	v_lshl_add_u64 v[88:89], s[92:93], 0, v[186:187]
	s_addk_i32 s33, 0x100
	v_lshl_add_u64 v[190:191], v[190:191], 0, 64
	v_fma_f32 v92, -v90, v91, 1.0
	v_fmac_f32_e32 v91, v92, v91
	v_div_scale_f32 v92, vcc, 1.0, v87, 1.0
	v_mul_f32_e32 v93, v92, v91
	v_fma_f32 v94, -v90, v93, v92
	v_fmac_f32_e32 v93, v94, v91
	v_fma_f32 v90, -v90, v93, v92
	v_div_fmas_f32 v90, v90, v91, v93
	v_div_fixup_f32 v87, v90, v87, 1.0
	v_div_scale_f32 v90, s[0:1], v86, v86, 1.0
	v_rcp_f32_e32 v91, v90
	s_cmpk_lg_i32 s33, 0x400
	v_fma_f32 v92, -v90, v91, 1.0
	v_fmac_f32_e32 v91, v92, v91
	v_div_scale_f32 v92, vcc, 1.0, v86, 1.0
	v_mul_f32_e32 v93, v92, v91
	v_fma_f32 v94, -v90, v93, v92
	v_fmac_f32_e32 v93, v94, v91
	v_fma_f32 v90, -v90, v93, v92
	v_div_fmas_f32 v90, v90, v91, v93
	v_div_fixup_f32 v86, v90, v86, 1.0
	v_mul_f32_e32 v92, v84, v86
	v_mul_f32_e32 v84, v85, v86
	v_mul_f32_e32 v84, v87, v84
	v_and_b32_e32 v86, 16, v168
	v_lshrrev_b32_e32 v87, 1, v86
	v_add_u32_e32 v86, v86, v87
	v_mov_b32_e32 v87, 0
	v_lshl_add_u64 v[90:91], v[88:89], 0, v[86:87]
	s_waitcnt vmcnt(3)
	v_permlane16_swap_b32_e32 v140, v142
	v_permlane16_swap_b32_e32 v141, v143
	v_pk_mul_f32 v[100:101], v[84:85], v[100:101] op_sel_hi:[0,1]
	v_pk_mul_f32 v[102:103], v[84:85], v[102:103] op_sel_hi:[0,1]
	v_lshlrev_b32_e32 v93, 16, v140
	v_and_b32_e32 v94, 0xffff0000, v140
	v_fmac_f32_e32 v100, v92, v93
	v_fmac_f32_e32 v101, v92, v94
	v_lshlrev_b32_e32 v93, 16, v141
	v_and_b32_e32 v94, 0xffff0000, v141
	v_fmac_f32_e32 v102, v92, v93
	v_fmac_f32_e32 v103, v92, v94
	v_pk_mul_f32 v[104:105], v[84:85], v[104:105] op_sel_hi:[0,1]
	v_pk_mul_f32 v[106:107], v[84:85], v[106:107] op_sel_hi:[0,1]
	v_lshlrev_b32_e32 v93, 16, v142
	v_and_b32_e32 v94, 0xffff0000, v142
	v_fmac_f32_e32 v104, v92, v93
	v_fmac_f32_e32 v105, v92, v94
	v_lshlrev_b32_e32 v93, 16, v143
	v_and_b32_e32 v94, 0xffff0000, v143
	v_fmac_f32_e32 v106, v92, v93
	v_fmac_f32_e32 v107, v92, v94
	v_cvt_pk_bf16_f32 v100, v100, v101
	v_cvt_pk_bf16_f32 v101, v102, v103
	v_cvt_pk_bf16_f32 v102, v104, v105
	v_cvt_pk_bf16_f32 v103, v106, v107
	s_nop 1
	v_permlane16_swap_b32_e32 v100, v102
	v_permlane16_swap_b32_e32 v101, v103
	global_store_dwordx4 v[90:91], v[100:103], off
	s_waitcnt vmcnt(3)
	v_permlane16_swap_b32_e32 v136, v138
	v_permlane16_swap_b32_e32 v137, v139
	v_pk_mul_f32 v[108:109], v[84:85], v[108:109] op_sel_hi:[0,1]
	v_pk_mul_f32 v[110:111], v[84:85], v[110:111] op_sel_hi:[0,1]
	v_lshlrev_b32_e32 v93, 16, v136
	v_and_b32_e32 v94, 0xffff0000, v136
	v_fmac_f32_e32 v108, v92, v93
	v_fmac_f32_e32 v109, v92, v94
	v_lshlrev_b32_e32 v93, 16, v137
	v_and_b32_e32 v94, 0xffff0000, v137
	v_fmac_f32_e32 v110, v92, v93
	v_fmac_f32_e32 v111, v92, v94
	v_pk_mul_f32 v[112:113], v[84:85], v[112:113] op_sel_hi:[0,1]
	v_pk_mul_f32 v[114:115], v[84:85], v[114:115] op_sel_hi:[0,1]
	v_lshlrev_b32_e32 v93, 16, v138
	v_and_b32_e32 v94, 0xffff0000, v138
	v_fmac_f32_e32 v112, v92, v93
	v_fmac_f32_e32 v113, v92, v94
	v_lshlrev_b32_e32 v93, 16, v139
	v_and_b32_e32 v94, 0xffff0000, v139
	v_fmac_f32_e32 v114, v92, v93
	v_fmac_f32_e32 v115, v92, v94
	v_cvt_pk_bf16_f32 v108, v108, v109
	v_cvt_pk_bf16_f32 v109, v110, v111
	v_cvt_pk_bf16_f32 v110, v112, v113
	v_cvt_pk_bf16_f32 v111, v114, v115
	s_nop 1
	v_permlane16_swap_b32_e32 v108, v110
	v_permlane16_swap_b32_e32 v109, v111
	global_store_dwordx4 v[90:91], v[108:111], off offset:64
	s_waitcnt vmcnt(3)
	v_permlane16_swap_b32_e32 v132, v134
	v_permlane16_swap_b32_e32 v133, v135
	v_pk_mul_f32 v[116:117], v[84:85], v[116:117] op_sel_hi:[0,1]
	v_pk_mul_f32 v[118:119], v[84:85], v[118:119] op_sel_hi:[0,1]
	v_lshlrev_b32_e32 v93, 16, v132
	v_and_b32_e32 v94, 0xffff0000, v132
	v_fmac_f32_e32 v116, v92, v93
	v_fmac_f32_e32 v117, v92, v94
	v_lshlrev_b32_e32 v93, 16, v133
	v_and_b32_e32 v94, 0xffff0000, v133
	v_fmac_f32_e32 v118, v92, v93
	v_fmac_f32_e32 v119, v92, v94
	v_pk_mul_f32 v[120:121], v[84:85], v[120:121] op_sel_hi:[0,1]
	v_pk_mul_f32 v[122:123], v[84:85], v[122:123] op_sel_hi:[0,1]
	v_lshlrev_b32_e32 v93, 16, v134
	v_and_b32_e32 v94, 0xffff0000, v134
	v_fmac_f32_e32 v120, v92, v93
	v_fmac_f32_e32 v121, v92, v94
	v_lshlrev_b32_e32 v93, 16, v135
	v_and_b32_e32 v94, 0xffff0000, v135
	v_fmac_f32_e32 v122, v92, v93
	v_fmac_f32_e32 v123, v92, v94
	v_cvt_pk_bf16_f32 v116, v116, v117
	v_cvt_pk_bf16_f32 v117, v118, v119
	v_cvt_pk_bf16_f32 v118, v120, v121
	v_cvt_pk_bf16_f32 v119, v122, v123
	s_nop 1
	v_permlane16_swap_b32_e32 v116, v118
	v_permlane16_swap_b32_e32 v117, v119
	global_store_dwordx4 v[90:91], v[116:119], off offset:128
	s_waitcnt vmcnt(3)
	v_permlane16_swap_b32_e32 v128, v130
	v_permlane16_swap_b32_e32 v129, v131
	v_pk_mul_f32 v[124:125], v[84:85], v[124:125] op_sel_hi:[0,1]
	v_pk_mul_f32 v[126:127], v[84:85], v[126:127] op_sel_hi:[0,1]
	v_lshlrev_b32_e32 v93, 16, v128
	v_and_b32_e32 v94, 0xffff0000, v128
	v_fmac_f32_e32 v124, v92, v93
	v_fmac_f32_e32 v125, v92, v94
	v_lshlrev_b32_e32 v93, 16, v129
	v_and_b32_e32 v94, 0xffff0000, v129
	v_fmac_f32_e32 v126, v92, v93
	v_fmac_f32_e32 v127, v92, v94
	v_pk_mul_f32 v[80:81], v[84:85], v[80:81] op_sel_hi:[0,1]
	v_pk_mul_f32 v[82:83], v[84:85], v[82:83] op_sel_hi:[0,1]
	v_lshlrev_b32_e32 v93, 16, v130
	v_and_b32_e32 v94, 0xffff0000, v130
	v_fmac_f32_e32 v80, v92, v93
	v_fmac_f32_e32 v81, v92, v94
	v_lshlrev_b32_e32 v93, 16, v131
	v_and_b32_e32 v94, 0xffff0000, v131
	v_fmac_f32_e32 v82, v92, v93
	v_fmac_f32_e32 v83, v92, v94
	v_cvt_pk_bf16_f32 v124, v124, v125
	v_cvt_pk_bf16_f32 v125, v126, v127
	v_cvt_pk_bf16_f32 v126, v80, v81
	v_cvt_pk_bf16_f32 v127, v82, v83
	s_nop 1
	v_permlane16_swap_b32_e32 v124, v126
	v_permlane16_swap_b32_e32 v125, v127
	global_store_dwordx4 v[90:91], v[124:127], off offset:192
	s_waitcnt lgkmcnt(0)
	s_barrier
	v_mov_b64_e32 v[126:127], v[66:67]
	v_mov_b64_e32 v[130:131], v[70:71]
	v_mov_b64_e32 v[134:135], v[74:75]
	v_mov_b64_e32 v[122:123], v[78:79]
	v_mov_b64_e32 v[124:125], v[64:65]
	v_mov_b64_e32 v[128:129], v[68:69]
	v_mov_b64_e32 v[132:133], v[72:73]
	v_mov_b64_e32 v[120:121], v[76:77]
	s_cbranch_scc0 .LBB0_163

; #define LAS __attribute__((address_space(3)))
; __device__ __forceinline__ unsigned cvt_pk_bf16(float lo, float hi) { unsigned r; asm volatile("v_cvt_pk_bf16_f32 %0, %1, %2" : "=v"(r) : "v"(lo), "v"(hi)); return r; }
;     ...
;         mx = fmaxf(mx, __shfl_xor(mx, 16)); mx = fmaxf(mx, __shfl_xor(mx, 32));
;         float l = 0.f;
; #pragma unroll
;         for (int t = 0; t < 10; ++t)
; #pragma unroll
;             for (int i = 0; i < 4; ++i) { const float p = __builtin_amdgcn_exp2f(s[t][i] - mx); s[t][i] = p; l += p; }
;         l += __shfl_xor(l, 16); l += __shfl_xor(l, 32);
;         bf16x8 pf[5];
; #pragma unroll
;         for (int b = 0; b < 5; ++b) { u32x4 u; u.x = pg8::cvt_pk_bf16(s[2 * b][0], s[2 * b][1]); u.y = pg8::cvt_pk_bf16(s[2 * b][2], s[2 * b][3]);
;             u.z = pg8::cvt_pk_bf16(s[2 * b + 1][0], s[2 * b + 1][1]); u.w = pg8::cvt_pk_bf16(s[2 * b + 1][2], s[2 * b + 1][3]); pf[b] = __builtin_bit_cast(bf16x8, u); }
;         float Lp = 0.f; u32x2 pv[8]; u32x2 gv[8];
;         if (PASS > 0) { Lp = LACC[(size_t)qrow * 16 + h];
; #pragma unroll
;             for (int db = 0; db < 8; ++db) pv[db] = *(const u32x2*)((const char*)OACC + ((unsigned)(h * MT + qrow) * 256u + (unsigned)(32 * db + 8 * fq))); }
;         if (PASS == 2) {
; #pragma unroll
;             for (int db = 0; db < 8; ++db) gv[db] = *(const u32x2*)((const char*)RB + ((unsigned)qrow * (unsigned)(LDB * 2) + (unsigned)(h * 256 + 32 * db + 8 * fq))); }
;         f32x4 o[8];
;         const int q4 = (lane & 15) >> 2, p4 = lane & 3;
;         LAS const unsigned char* vbase = lds + VOFF + (16 * ts + 4 * fq + q4) * VPITCH + p4 * 8;
;         {
;             s16x4 vl[2][5], vh[2][5];
.LBB0_459:
	s_waitcnt lgkmcnt(2)
	ds_bpermute_b32 v80, v219, v160
	v_max_f32_e32 v81, v160, v160
	v_add_u32_e32 v186, s33, v230
	s_waitcnt lgkmcnt(0)
	v_max_f32_e32 v80, v80, v80
	v_max_f32_e32 v80, v81, v80
	ds_bpermute_b32 v81, v220, v80
	s_waitcnt lgkmcnt(0)
	v_max_f32_e32 v81, v81, v81
	v_max_f32_e32 v160, v80, v81
	v_sub_f32_e32 v80, v120, v160
	v_exp_f32_e32 v100, v80
	v_sub_f32_e32 v80, v125, v160
	v_exp_f32_e32 v105, v80
	v_sub_f32_e32 v80, v126, v160
	v_exp_f32_e32 v106, v80
	v_sub_f32_e32 v80, v127, v160
	v_exp_f32_e32 v107, v80
	v_sub_f32_e32 v80, v128, v160
	v_exp_f32_e32 v108, v80
	v_sub_f32_e32 v80, v129, v160
	v_exp_f32_e32 v109, v80
	v_sub_f32_e32 v80, v130, v160
	v_exp_f32_e32 v110, v80
	v_sub_f32_e32 v80, v131, v160
	v_exp_f32_e32 v111, v80
	v_sub_f32_e32 v80, v132, v160
	v_exp_f32_e32 v112, v80
	v_sub_f32_e32 v80, v133, v160
	v_exp_f32_e32 v113, v80
	v_sub_f32_e32 v80, v134, v160
	v_exp_f32_e32 v114, v80
	v_sub_f32_e32 v80, v135, v160
	v_exp_f32_e32 v115, v80
	v_sub_f32_e32 v80, v136, v160
	v_exp_f32_e32 v116, v80
	v_sub_f32_e32 v80, v137, v160
	v_exp_f32_e32 v117, v80
	v_sub_f32_e32 v80, v138, v160
	v_exp_f32_e32 v118, v80
	v_sub_f32_e32 v80, v139, v160
	v_exp_f32_e32 v119, v80
	v_sub_f32_e32 v80, v140, v160
	v_exp_f32_e32 v120, v80
	v_sub_f32_e32 v80, v141, v160
	v_sub_f32_e32 v81, v121, v160
	v_exp_f32_e32 v121, v80
	v_sub_f32_e32 v80, v142, v160
	v_sub_f32_e32 v82, v122, v160
	v_exp_f32_e32 v122, v80
	v_sub_f32_e32 v80, v143, v160
	v_sub_f32_e32 v83, v123, v160
	v_exp_f32_e32 v123, v80
	v_sub_f32_e32 v80, v144, v160
	v_sub_f32_e32 v84, v124, v160
	v_exp_f32_e32 v124, v80
	v_sub_f32_e32 v80, v145, v160
	v_exp_f32_e32 v125, v80
	v_sub_f32_e32 v80, v146, v160
	v_exp_f32_e32 v126, v80
	v_sub_f32_e32 v80, v147, v160
	v_exp_f32_e32 v127, v80
	v_sub_f32_e32 v80, v148, v160
	v_exp_f32_e32 v144, v80
	v_sub_f32_e32 v80, v149, v160
	v_exp_f32_e32 v145, v80
	v_sub_f32_e32 v80, v150, v160
	v_exp_f32_e32 v146, v80
	v_sub_f32_e32 v80, v151, v160
	v_exp_f32_e32 v147, v80
	v_sub_f32_e32 v80, v152, v160
	v_exp_f32_e32 v148, v80
	v_sub_f32_e32 v80, v153, v160
	v_exp_f32_e32 v149, v80
	v_sub_f32_e32 v80, v154, v160
	v_exp_f32_e32 v150, v80
	v_sub_f32_e32 v80, v155, v160
	v_exp_f32_e32 v151, v80
	v_sub_f32_e32 v80, v156, v160
	v_exp_f32_e32 v152, v80
	v_sub_f32_e32 v80, v157, v160
	v_exp_f32_e32 v153, v80
	v_sub_f32_e32 v80, v158, v160
	v_exp_f32_e32 v154, v80
	v_sub_f32_e32 v80, v159, v160
	v_exp_f32_e32 v101, v81
	v_exp_f32_e32 v102, v82
	v_exp_f32_e32 v103, v83
	v_exp_f32_e32 v104, v84
	v_exp_f32_e32 v155, v80
	v_cvt_pk_bf16_f32 v80, v100, v101
	v_cvt_pk_bf16_f32 v81, v102, v103
	v_cvt_pk_bf16_f32 v82, v104, v105
	v_cvt_pk_bf16_f32 v83, v106, v107
	v_cvt_pk_bf16_f32 v84, v108, v109
	v_cvt_pk_bf16_f32 v85, v110, v111
	v_cvt_pk_bf16_f32 v86, v112, v113
	v_cvt_pk_bf16_f32 v87, v114, v115
	v_cvt_pk_bf16_f32 v88, v116, v117
	v_cvt_pk_bf16_f32 v89, v118, v119
	v_cvt_pk_bf16_f32 v90, v120, v121
	v_cvt_pk_bf16_f32 v91, v122, v123
	v_cvt_pk_bf16_f32 v92, v124, v125
	v_cvt_pk_bf16_f32 v93, v126, v127
	v_cvt_pk_bf16_f32 v94, v144, v145
	v_cvt_pk_bf16_f32 v95, v146, v147
	v_cvt_pk_bf16_f32 v96, v148, v149
	v_cvt_pk_bf16_f32 v97, v150, v151
	v_cvt_pk_bf16_f32 v98, v152, v153
	v_cvt_pk_bf16_f32 v99, v154, v155
	global_load_dword v161, v[190:191], off
	v_and_b32_e32 v232, 16, v168
	v_lshrrev_b32_e32 v233, 1, v232
	v_add3_u32 v232, v186, v232, v233
	global_load_dwordx4 v[140:143], v232, s[92:93]
	global_load_dwordx4 v[136:139], v232, s[92:93] offset:64
	global_load_dwordx4 v[132:135], v232, s[92:93] offset:128
	global_load_dwordx4 v[128:131], v232, s[92:93] offset:192
	v_add_f32_e32 v100, 0, v100
	v_add_f32_e32 v100, v101, v100
	v_add_f32_e32 v100, v102, v100
	v_add_f32_e32 v100, v103, v100
	v_add_f32_e32 v100, v104, v100
	v_add_f32_e32 v100, v105, v100
	v_add_f32_e32 v100, v106, v100
	v_add_f32_e32 v100, v107, v100
	v_add_f32_e32 v100, v108, v100
	v_add_f32_e32 v100, v109, v100
	v_add_f32_e32 v100, v110, v100
	v_add_f32_e32 v100, v111, v100
	v_add_f32_e32 v100, v112, v100
	v_add_f32_e32 v100, v113, v100
	v_add_f32_e32 v100, v114, v100
	v_add_f32_e32 v100, v115, v100
	v_add_f32_e32 v100, v116, v100
	v_add_f32_e32 v100, v117, v100
	v_add_f32_e32 v100, v118, v100
	v_add_f32_e32 v100, v119, v100
	v_add_f32_e32 v100, v120, v100
	v_add_f32_e32 v100, v121, v100
	v_add_f32_e32 v100, v122, v100
	v_add_f32_e32 v100, v123, v100
	v_add_f32_e32 v100, v124, v100
	v_add_f32_e32 v100, v125, v100
	v_add_f32_e32 v100, v126, v100
	v_add_f32_e32 v100, v127, v100
	v_add_f32_e32 v100, v144, v100
	v_add_f32_e32 v100, v145, v100
	v_add_f32_e32 v100, v146, v100
	v_add_f32_e32 v100, v147, v100
	v_add_f32_e32 v100, v148, v100
	v_add_f32_e32 v100, v149, v100
	v_add_f32_e32 v100, v150, v100
	v_add_f32_e32 v100, v151, v100
	v_add_f32_e32 v100, v152, v100
	v_add_f32_e32 v100, v153, v100
	v_add_f32_e32 v100, v154, v100
	v_add_f32_e32 v100, v155, v100
	ds_bpermute_b32 v101, v219, v100
	s_waitcnt lgkmcnt(0)
	v_add_f32_e32 v166, v100, v101
	ds_read_b64_tr_b16 v[102:103], v188 offset:4608
	ds_read_b64_tr_b16 v[100:101], v188
	ds_read_b64_tr_b16 v[106:107], v188 offset:4640
	ds_read_b64_tr_b16 v[104:105], v188 offset:32
	ds_read_b64_tr_b16 v[108:109], v188 offset:9216
	ds_read_b64_tr_b16 v[110:111], v188 offset:13824
	ds_read_b64_tr_b16 v[114:115], v188 offset:13856
	ds_read_b64_tr_b16 v[112:113], v188 offset:9248
	ds_read_b64_tr_b16 v[116:117], v188 offset:18432
	ds_read_b64_tr_b16 v[118:119], v188 offset:23040
	ds_read_b64_tr_b16 v[122:123], v188 offset:23072
	ds_read_b64_tr_b16 v[120:121], v188 offset:18464
	ds_read_b64_tr_b16 v[124:125], v188 offset:27648
	ds_read_b64_tr_b16 v[126:127], v188 offset:32256
	ds_read_b64_tr_b16 v[146:147], v188 offset:32288
	ds_read_b64_tr_b16 v[144:145], v188 offset:27680
	ds_read_b64_tr_b16 v[148:149], v188 offset:36864
	ds_read_b64_tr_b16 v[150:151], v188 offset:41472
	ds_read_b64_tr_b16 v[154:155], v188 offset:41504
	ds_read_b64_tr_b16 v[152:153], v188 offset:36896
	ds_bpermute_b32 v167, v220, v166
	s_waitcnt lgkmcnt(14)
; #define ATT_LDV(BUF, DB) _Pragma("unroll") for (int b = 0; b < 5; ++b) { vl[BUF][b] = vtr(vbase + (32 * b) * VPITCH + (DB) * 32); vh[BUF][b] = vtr(vbase + (32 * b + 16) * VPITCH + (DB) * 32); }
;     ...
;             ATT_LDV(0, 0)
; #pragma unroll
;             for (int db = 0; db < 8; ++db) {
;                 if (db + 1 < 8) { ATT_LDV((db + 1) & 1, db + 1) }
;                 __builtin_amdgcn_sched_barrier(0);
;                 o[db] = (f32x4){0.f, 0.f, 0.f, 0.f};
; #pragma unroll
;                 for (int b = 0; b < 5; ++b) { const s16x4 lo = vl[db & 1][b], hi = vh[db & 1][b];
;                     const bf16x8 vf = (bf16x8){lo[0], lo[1], lo[2], lo[3], hi[0], hi[1], hi[2], hi[3]};
;                     o[db] = __builtin_amdgcn_mfma_f32_16x16x32_bf16(vf, pf[b], o[db], 0, 0, 0); }
;                 __builtin_amdgcn_sched_barrier(0);
;             }
;     ...
;         }
;         const float rl = 1.0f / l;
;         float Lc = mx + __builtin_amdgcn_logf(l);
;         float wb = rl, wa = 0.f;
;         if (PASS > 0) { const float Lm = fmaxf(Lp, Lc);
;             const float ea = __builtin_amdgcn_exp2f(Lp - Lm), eb = __builtin_amdgcn_exp2f(Lc - Lm), den = ea + eb, rd = 1.0f / den;
;             wa = ea * rd; wb = eb * rd * rl; Lc = Lm + __builtin_amdgcn_logf(den); }
;         if (PASS < 2) { if (fq == 0) LACC[(size_t)qrow * 16 + h] = Lc; }
	v_mfma_f32_16x16x32_bf16 v[100:103], v[100:103], v[80:83], 0
	v_mfma_f32_16x16x32_bf16 v[100:103], v[108:111], v[84:87], v[100:103]
	s_waitcnt lgkmcnt(11)
	v_mfma_f32_16x16x32_bf16 v[100:103], v[116:119], v[88:91], v[100:103]
	s_waitcnt lgkmcnt(7)
	v_mfma_f32_16x16x32_bf16 v[100:103], v[124:127], v[92:95], v[100:103]
	s_waitcnt lgkmcnt(3)
	v_mfma_f32_16x16x32_bf16 v[100:103], v[148:151], v[96:99], v[100:103]
	ds_read_b64_tr_b16 v[108:109], v188 offset:9280
	ds_read_b64_tr_b16 v[110:111], v188 offset:13888
	ds_read_b64_tr_b16 v[116:117], v188 offset:18496
	ds_read_b64_tr_b16 v[118:119], v188 offset:23104
	ds_read_b64_tr_b16 v[124:125], v188 offset:27712
	ds_read_b64_tr_b16 v[126:127], v188 offset:32320
	ds_read_b64_tr_b16 v[148:149], v188 offset:64
	ds_read_b64_tr_b16 v[150:151], v188 offset:4672
	ds_read_b64_tr_b16 v[156:157], v188 offset:36928
	ds_read_b64_tr_b16 v[158:159], v188 offset:41536
	v_mfma_f32_16x16x32_bf16 v[104:107], v[104:107], v[80:83], 0
	v_mfma_f32_16x16x32_bf16 v[104:107], v[112:115], v[84:87], v[104:107]
	v_mfma_f32_16x16x32_bf16 v[104:107], v[120:123], v[88:91], v[104:107]
	v_mfma_f32_16x16x32_bf16 v[104:107], v[144:147], v[92:95], v[104:107]
	s_waitcnt lgkmcnt(11)
	v_mfma_f32_16x16x32_bf16 v[104:107], v[152:155], v[96:99], v[104:107]
	ds_read_b64_tr_b16 v[112:113], v188 offset:9312
	ds_read_b64_tr_b16 v[114:115], v188 offset:13920
	ds_read_b64_tr_b16 v[120:121], v188 offset:18528
	ds_read_b64_tr_b16 v[122:123], v188 offset:23136
	ds_read_b64_tr_b16 v[144:145], v188 offset:27744
	ds_read_b64_tr_b16 v[146:147], v188 offset:32352
	ds_read_b64_tr_b16 v[152:153], v188 offset:96
	ds_read_b64_tr_b16 v[154:155], v188 offset:4704
	ds_read_b64_tr_b16 v[162:163], v188 offset:36960
	ds_read_b64_tr_b16 v[164:165], v188 offset:41568
	s_waitcnt lgkmcnt(12)
	v_mfma_f32_16x16x32_bf16 v[148:151], v[148:151], v[80:83], 0
	v_mfma_f32_16x16x32_bf16 v[108:111], v[108:111], v[84:87], v[148:151]
	v_mfma_f32_16x16x32_bf16 v[108:111], v[116:119], v[88:91], v[108:111]
	v_mfma_f32_16x16x32_bf16 v[108:111], v[124:127], v[92:95], v[108:111]
	s_waitcnt lgkmcnt(10)
	v_mfma_f32_16x16x32_bf16 v[108:111], v[156:159], v[96:99], v[108:111]
	ds_read_b64_tr_b16 v[116:117], v188 offset:9344
	ds_read_b64_tr_b16 v[118:119], v188 offset:13952
	ds_read_b64_tr_b16 v[124:125], v188 offset:18560
	ds_read_b64_tr_b16 v[126:127], v188 offset:23168
	ds_read_b64_tr_b16 v[148:149], v188 offset:27776
	ds_read_b64_tr_b16 v[150:151], v188 offset:32384
	ds_read_b64_tr_b16 v[156:157], v188 offset:128
	ds_read_b64_tr_b16 v[158:159], v188 offset:4736
	ds_read_b64_tr_b16 v[232:233], v188 offset:36992
	ds_read_b64_tr_b16 v[234:235], v188 offset:41600
	s_waitcnt lgkmcnt(12)
	v_mfma_f32_16x16x32_bf16 v[152:155], v[152:155], v[80:83], 0
	v_mfma_f32_16x16x32_bf16 v[112:115], v[112:115], v[84:87], v[152:155]
	v_mfma_f32_16x16x32_bf16 v[112:115], v[120:123], v[88:91], v[112:115]
	v_mfma_f32_16x16x32_bf16 v[112:115], v[144:147], v[92:95], v[112:115]
	s_waitcnt lgkmcnt(10)
	v_mfma_f32_16x16x32_bf16 v[112:115], v[162:165], v[96:99], v[112:115]
	ds_read_b64_tr_b16 v[120:121], v188 offset:9376
	ds_read_b64_tr_b16 v[122:123], v188 offset:13984
	ds_read_b64_tr_b16 v[144:145], v188 offset:18592
	ds_read_b64_tr_b16 v[146:147], v188 offset:23200
	ds_read_b64_tr_b16 v[152:153], v188 offset:27808
	ds_read_b64_tr_b16 v[154:155], v188 offset:32416
	ds_read_b64_tr_b16 v[162:163], v188 offset:160
	ds_read_b64_tr_b16 v[164:165], v188 offset:4768
	ds_read_b64_tr_b16 v[236:237], v188 offset:37024
	ds_read_b64_tr_b16 v[238:239], v188 offset:41632
	s_waitcnt lgkmcnt(12)
	v_mfma_f32_16x16x32_bf16 v[156:159], v[156:159], v[80:83], 0
	v_mfma_f32_16x16x32_bf16 v[116:119], v[116:119], v[84:87], v[156:159]
	v_mfma_f32_16x16x32_bf16 v[116:119], v[124:127], v[88:91], v[116:119]
	v_mfma_f32_16x16x32_bf16 v[116:119], v[148:151], v[92:95], v[116:119]
	s_waitcnt lgkmcnt(10)
	v_mfma_f32_16x16x32_bf16 v[116:119], v[232:235], v[96:99], v[116:119]
	ds_read_b64_tr_b16 v[124:125], v188 offset:9408
	ds_read_b64_tr_b16 v[126:127], v188 offset:14016
	ds_read_b64_tr_b16 v[148:149], v188 offset:18624
	ds_read_b64_tr_b16 v[150:151], v188 offset:23232
	ds_read_b64_tr_b16 v[156:157], v188 offset:27840
	ds_read_b64_tr_b16 v[158:159], v188 offset:32448
	ds_read_b64_tr_b16 v[232:233], v188 offset:192
	ds_read_b64_tr_b16 v[234:235], v188 offset:4800
	ds_read_b64_tr_b16 v[240:241], v188 offset:37056
	ds_read_b64_tr_b16 v[242:243], v188 offset:41664
	s_waitcnt lgkmcnt(12)
	v_mfma_f32_16x16x32_bf16 v[162:165], v[162:165], v[80:83], 0
	v_mfma_f32_16x16x32_bf16 v[120:123], v[120:123], v[84:87], v[162:165]
	v_mfma_f32_16x16x32_bf16 v[120:123], v[144:147], v[88:91], v[120:123]
	v_mfma_f32_16x16x32_bf16 v[120:123], v[152:155], v[92:95], v[120:123]
	s_waitcnt lgkmcnt(10)
	v_mfma_f32_16x16x32_bf16 v[120:123], v[236:239], v[96:99], v[120:123]
	ds_read_b64_tr_b16 v[144:145], v188 offset:9440
	ds_read_b64_tr_b16 v[146:147], v188 offset:14048
	ds_read_b64_tr_b16 v[152:153], v188 offset:18656
	ds_read_b64_tr_b16 v[154:155], v188 offset:23264
	ds_read_b64_tr_b16 v[162:163], v188 offset:27872
	ds_read_b64_tr_b16 v[164:165], v188 offset:32480
	ds_read_b64_tr_b16 v[236:237], v188 offset:224
	ds_read_b64_tr_b16 v[238:239], v188 offset:4832
	ds_read_b64_tr_b16 v[244:245], v188 offset:37088
	ds_read_b64_tr_b16 v[246:247], v188 offset:41696
	s_waitcnt lgkmcnt(12)
	v_mfma_f32_16x16x32_bf16 v[232:235], v[232:235], v[80:83], 0
	v_mfma_f32_16x16x32_bf16 v[124:127], v[124:127], v[84:87], v[232:235]
	v_mfma_f32_16x16x32_bf16 v[124:127], v[148:151], v[88:91], v[124:127]
	v_mfma_f32_16x16x32_bf16 v[124:127], v[156:159], v[92:95], v[124:127]
	s_waitcnt lgkmcnt(10)
	v_mfma_f32_16x16x32_bf16 v[124:127], v[240:243], v[96:99], v[124:127]
	s_waitcnt lgkmcnt(2)
	v_mfma_f32_16x16x32_bf16 v[80:83], v[236:239], v[80:83], 0
	v_mfma_f32_16x16x32_bf16 v[80:83], v[144:147], v[84:87], v[80:83]
	v_mfma_f32_16x16x32_bf16 v[80:83], v[152:155], v[88:91], v[80:83]
	v_mfma_f32_16x16x32_bf16 v[80:83], v[162:165], v[92:95], v[80:83]
	s_waitcnt lgkmcnt(0)
	v_mfma_f32_16x16x32_bf16 v[80:83], v[244:247], v[96:99], v[80:83]
	v_add_f32_e32 v87, v166, v167
	v_log_f32_e32 v84, v87
	s_nop 0
	v_add_f32_e32 v85, v160, v84
	s_waitcnt vmcnt(4)
	v_max_f32_e32 v84, v161, v161
	v_max_f32_e32 v88, v84, v85
	v_sub_f32_e32 v84, v161, v88
	v_sub_f32_e32 v85, v85, v88
	v_exp_f32_e32 v84, v84
	v_exp_f32_e32 v85, v85
	s_nop 0
	v_add_f32_e32 v86, v84, v85
	s_and_saveexec_b64 s[0:1], s[6:7]
	s_cbranch_execz .LBB0_364
	v_log_f32_e32 v89, v86
	s_nop 0
	v_add_f32_e32 v88, v88, v89
	global_store_dword v[190:191], v88, off
	s_branch .LBB0_364
